# defer x->bf16 conversion of segments 1..3 from prep phase into the idle workgroups of the up-projection tail
# speedup vs baseline: 1.0087x; 1.0077x over previous
; __device__ __forceinline__ unsigned cvt_pk_bf16(float lo, float hi) { unsigned r; asm volatile("v_cvt_pk_bf16_f32 %0, %1, %2" : "=v"(r) : "v"(lo), "v"(hi)); return r; }
; #define GAS __attribute__((address_space(1)))
; __device__ __forceinline__ void phase_prep(const Params& P, unsigned char* smem) {
;     ...
;     GAS bf16* xb = (GAS bf16*)(ws + WS_XB); GAS float* rstd1 = (GAS float*)(ws + WS_RSTD1);
;     for (int rid = gw; rid < NSEG * RSB; rid += NGW) {
;         const int s = rid / RSB, lr = rid % RSB; const float* src = nullptr;
;         if (lr < RS) src = P.x + ((size_t)(lr / TSEG) * SEQ + (size_t)s * TSEG + (lr % TSEG)) * DM;
;         else if (s == 0) { if (lr >= RS + 48 && lr < RS + 64) src = P.meta + (size_t)(lr - RS - 48) * DM; }
;         else continue;
;         GAS v2u* o8 = (GAS v2u*)(xb + (size_t)rid * DM) + lane; float ss = 0.f;
;         if (src) { const f32x4* xr = (const f32x4*)src + lane;
; #pragma unroll
;             for (int j = 0; j < 8; ++j) { const f32x4 v = __builtin_nontemporal_load((const GAS f32x4*)xr + 64 * j); ss += (v[0] * v[0] + v[1] * v[1]) + (v[2] * v[2] + v[3] * v[3]); v2u o; o.x = cvt_pk_bf16(v[0], v[1]); o.y = cvt_pk_bf16(v[2], v[3]); o8[64 * j] = o; } }
;         else {
; #pragma unroll
;             for (int j = 0; j < 8; ++j) { v2u o; o.x = 0u; o.y = 0u; o8[64 * j] = o; } }
;         ss = wave_sum(ss);
;         if (lane == 0) rstd1[rid] = rsqrtf(ss * (1.f / DM) + EPS);
;     }
.LBB0_45:
	s_or_b64 exec, exec, s[4:5]
	s_movk_i32 s4, 0x2100
	v_cmp_gt_i32_e32 vcc, s4, v2
	v_mbcnt_lo_u32_b32 v16, -1, 0
	s_and_saveexec_b64 s[4:5], vcc
	v_readlane_b32 s36, v252, 8
	v_readlane_b32 s37, v252, 9
	v_readlane_b32 s38, v252, 10
	v_readlane_b32 s39, v252, 11
	v_readlane_b32 s44, v252, 16
	v_readlane_b32 s45, v252, 17
	v_readlane_b32 s40, v252, 12
	v_readlane_b32 s41, v252, 13
	v_readlane_b32 s42, v252, 14
	v_readlane_b32 s43, v252, 15
	v_readlane_b32 s46, v252, 18
	v_readlane_b32 s47, v252, 19
	v_readlane_b32 s48, v252, 20
	v_readlane_b32 s49, v252, 21
	v_readlane_b32 s50, v252, 22
	v_readlane_b32 s51, v252, 23
	s_cbranch_execz .LBB0_61
	s_add_u32 s8, s0, 0x134c0000
	v_mov_b32_e32 v5, 0
	s_addc_u32 s9, s1, 0
	v_lshl_add_u64 v[8:9], s[0:1], 0, v[4:5]
	s_mov_b64 s[0:1], 0xb0c0000
	v_lshlrev_b32_e32 v1, 11, v1
	s_mov_b32 s12, 0xfbfa0000
	v_lshl_add_u64 v[8:9], v[8:9], 0, s[0:1]
	v_cmp_eq_u32_e32 vcc, 0, v6
	v_lshl_add_u32 v1, s2, 14, v1
	s_lshl_b32 s22, s3, 11
	s_mov_b64 s[10:11], 0
	s_mov_b32 s23, 0x3e0f83e1
	s_movk_i32 s24, 0x1fff
	s_movk_i32 s25, 0x41ff
	s_movk_i32 s26, 0x2030
	s_mov_b32 s13, -1
	v_lshlrev_b32_e32 v6, 4, v6
	s_movk_i32 s27, 0x1000
	v_mov_b32_e32 v17, 0x358637bd
	s_mov_b32 s28, 0x800000
	s_movk_i32 s29, 0x20ff
	s_mov_b32 s14, 0
	v_mbcnt_hi_u32_b32 v18, -1, v16
	s_branch .LBB0_48

; #define GAS __attribute__((address_space(1)))
; __global__ void __launch_bounds__(NTHREADS, 2) hybrid_fwd(Params P) {
;     ...
;     for (int seg = 0; seg < NSEG; ++seg) {
;         ws = launder_s((const void*)ws);
;         { Epi1 E; E.O = (GAS bf16*)(ws + WS_PROJ); E.rstd = (const GAS float*)(ws + WS_RSTD1) + (size_t)seg * RSB;
;           for (int rep = 0; rep < REP_G1; ++rep) run_gemm(smem, (const GAS bf16*)(ws + WS_XB) + (size_t)seg * RSB * DM, (const GAS bf16*)(ws + WS_WIN), RS, NPROJ, DM, E); }
;         for (int rep = 0; rep < REP_SIDE; ++rep) side_gemm1(P, seg);
;         xcd_barrier(xb);
;         for (int rep = 0; rep < REP_ELT; ++rep) phase_conv(P, seg);
;         xcd_barrier(xb);
;         for (int rep = 0; rep < REP_SSD; ++rep) phase_ssd(P, seg, smem);
;         xcd_barrier(xb);
;         phase_gnorm(P, seg);
;         ws = launder_s((const void*)ws);
;         { EpiGate<0> E; E.proj = (const GAS bf16*)(ws + WS_PROJ); E.bgate = P.b_gate; E.ta = (GAS bf16*)(ws + WS_TA); E.mix = (GAS bf16*)(ws + WS_MIX);
;           for (int rep = 0; rep < REP_GX; ++rep) run_gemm(smem, (const GAS bf16*)(ws + WS_YA), (const GAS bf16*)(ws + WS_WA), RS, DM, DM, E); }
;         if (seg == 0) side_gemm2(P, smem);
;         xcd_barrier(xb);
;         ws = launder_s((const void*)ws);
;         { EpiGate<1> E; E.proj = (const GAS bf16*)(ws + WS_PROJ); E.bgate = P.b_gate; E.ta = (GAS bf16*)(ws + WS_TA); E.mix = (GAS bf16*)(ws + WS_MIX);
;           for (int rep = 0; rep < REP_GX; ++rep) run_gemm(smem, (const GAS bf16*)(ws + WS_YPRE), (const GAS bf16*)(ws + WS_WM), RS, DM, DINNER, E); }
;         if (seg == 0) side_gemm3(P, smem);
;         xcd_barrier(xb);
;         ws = launder_s((const void*)ws);
;         { Epi4 E; E.x = P.x; E.meta = P.meta; E.h1b = (GAS bf16*)(ws + WS_H1B); E.ssq = (GAS float*)(ws + WS_SSQ2); E.seg = seg;
;           for (int rep = 0; rep < REP_GX; ++rep) run_gemm(smem, (const GAS bf16*)(ws + WS_MIX), (const GAS bf16*)(ws + WS_WO), RS, DM, DM, E); }
;         if (seg == 0) side_gemm4(P, smem);
;         xcd_barrier(xb);
;         ws = launder_s((const void*)ws);
;         { Epi5 E; E.act = (GAS bf16*)(ws + WS_ACT); E.ssq = (const GAS float*)(ws + WS_SSQ2); E.cw = P.ffn_conv_w; E.cb = P.ffn_conv_b; E.xch = (LAS float*)(smem + LDS_XCH);
;           E.eu = (GAS float*)(ws + WS_EU) + (size_t)(seg & 1) * (32 * 4 * DFF); E.ev = (GAS float*)(ws + WS_EV);
.Ltramp76:
	s_branch .LBB0_76
.Ltramp75:
	s_branch .LBB0_75

; __device__ __forceinline__ unsigned cvt_pk_bf16(float lo, float hi) { unsigned r; asm volatile("v_cvt_pk_bf16_f32 %0, %1, %2" : "=v"(r) : "v"(lo), "v"(hi)); return r; }
; #define GAS __attribute__((address_space(1)))
; __device__ __forceinline__ void phase_prep(const Params& P, unsigned char* smem) {
;     ...
;     for (int rid = gw; rid < NSEG * RSB; rid += NGW) {
;         const int s = rid / RSB, lr = rid % RSB; const float* src = nullptr;
;         if (lr < RS) src = P.x + ((size_t)(lr / TSEG) * SEQ + (size_t)s * TSEG + (lr % TSEG)) * DM;
;         else if (s == 0) { if (lr >= RS + 48 && lr < RS + 64) src = P.meta + (size_t)(lr - RS - 48) * DM; }
;         else continue;
;         GAS v2u* o8 = (GAS v2u*)(xb + (size_t)rid * DM) + lane; float ss = 0.f;
;         if (src) { const f32x4* xr = (const f32x4*)src + lane;
; #pragma unroll
;             for (int j = 0; j < 8; ++j) { const f32x4 v = __builtin_nontemporal_load((const GAS f32x4*)xr + 64 * j); ss += (v[0] * v[0] + v[1] * v[1]) + (v[2] * v[2] + v[3] * v[3]); v2u o; o.x = cvt_pk_bf16(v[0], v[1]); o.y = cvt_pk_bf16(v[2], v[3]); o8[64 * j] = o; } }
;         else {
; #pragma unroll
;             for (int j = 0; j < 8; ++j) { v2u o; o.x = 0u; o.y = 0u; o8[64 * j] = o; } }
;         ss = wave_sum(ss);
;         if (lane == 0) rstd1[rid] = rsqrtf(ss * (1.f / DM) + EPS);
.LBB0_693:
	v_readlane_b32 s0, v254, 38
	s_nop 3
	s_cmp_gt_u32 s0, 2
	s_cbranch_scc1 .Lxc_done
	s_cmp_lt_u32 s2, 0x60
	s_cbranch_scc1 .Lxc_done
	s_mov_b64 s[36:37], exec
	s_mov_b64 exec, -1
	s_add_i32 s0, s0, 1
	v_readfirstlane_b32 s1, v172
	v_readlane_b32 s16, v252, 8
	v_readlane_b32 s17, v252, 9
	s_lshr_b32 s1, s1, 6
	s_sub_i32 s9, s2, 0x60
	s_lshl_b32 s9, s9, 3
	s_add_i32 s9, s9, s1
	s_sub_i32 s14, s82, 0x60
	s_lshl_b32 s14, s14, 3
	s_lshl_b32 s15, s0, 12
	s_mul_i32 s23, s0, 0x2100
	s_add_u32 s48, s80, 0xb0c0000
	s_addc_u32 s49, s81, 0
	s_add_u32 s52, s80, 0x134c0000
	s_addc_u32 s53, s81, 0
	v_and_b32_e32 v31, 63, v172
	v_lshlrev_b32_e32 v28, 4, v31
	v_lshlrev_b32_e32 v30, 3, v31
	v_add_u32_e32 v29, 0x1000, v28
	v_mov_b32_e32 v31, 0
	v_mov_b32_e32 v32, 0x3a000000
	v_mov_b32_e32 v33, 0x358637bd
	s_cmp_lt_u32 s9, 0x2000
	s_cbranch_scc0 .Lxc_exit
	s_lshr_b32 s20, s9, 12
	s_and_b32 s22, s9, 0xfff
	s_lshl_b32 s20, s20, 14
	s_add_i32 s20, s20, s22
	s_add_i32 s20, s20, s15
	s_lshl_b32 s20, s20, 13
	s_add_u32 s40, s16, s20
	s_addc_u32 s41, s17, 0
	global_load_dwordx4 v[40:43], v28, s[40:41] nt
	global_load_dwordx4 v[44:47], v28, s[40:41] offset:1024 nt
	global_load_dwordx4 v[48:51], v28, s[40:41] offset:2048 nt
	global_load_dwordx4 v[52:55], v28, s[40:41] offset:3072 nt
	global_load_dwordx4 v[56:59], v29, s[40:41] nt
	global_load_dwordx4 v[60:63], v29, s[40:41] offset:1024 nt
	global_load_dwordx4 v[64:67], v29, s[40:41] offset:2048 nt
	global_load_dwordx4 v[68:71], v29, s[40:41] offset:3072 nt
.Lxc_loop:
	s_add_i32 s54, s9, s14
	s_cmp_lt_u32 s54, 0x2000
	s_cbranch_scc0 .Lxc_lastA
	s_lshr_b32 s20, s54, 12
	s_and_b32 s22, s54, 0xfff
	s_lshl_b32 s20, s20, 14
	s_add_i32 s20, s20, s22
	s_add_i32 s20, s20, s15
	s_lshl_b32 s20, s20, 13
	s_add_u32 s40, s16, s20
	s_addc_u32 s41, s17, 0
	global_load_dwordx4 v[72:75], v28, s[40:41] nt
	global_load_dwordx4 v[76:79], v28, s[40:41] offset:1024 nt
	global_load_dwordx4 v[80:83], v28, s[40:41] offset:2048 nt
	global_load_dwordx4 v[84:87], v28, s[40:41] offset:3072 nt
	global_load_dwordx4 v[88:91], v29, s[40:41] nt
	global_load_dwordx4 v[92:95], v29, s[40:41] offset:1024 nt
	global_load_dwordx4 v[96:99], v29, s[40:41] offset:2048 nt
	global_load_dwordx4 v[100:103], v29, s[40:41] offset:3072 nt
	s_waitcnt vmcnt(8)
	s_add_i32 s22, s9, s23
	s_lshl_b32 s24, s22, 12
	s_add_u32 s42, s48, s24
	s_addc_u32 s43, s49, 0
	s_lshl_b32 s24, s22, 2
	s_add_u32 s50, s52, s24
	s_addc_u32 s51, s53, 0
	v_pk_mul_f32 v[24:25], v[40:41], v[40:41]
	v_cvt_pk_bf16_f32 v8, v40, v41
	v_pk_fma_f32 v[24:25], v[42:43], v[42:43], v[24:25]
	v_cvt_pk_bf16_f32 v9, v42, v43
	global_store_dwordx2 v30, v[8:9], s[42:43]
	v_pk_fma_f32 v[24:25], v[44:45], v[44:45], v[24:25]
	v_cvt_pk_bf16_f32 v10, v44, v45
	v_pk_fma_f32 v[24:25], v[46:47], v[46:47], v[24:25]
	v_cvt_pk_bf16_f32 v11, v46, v47
	global_store_dwordx2 v30, v[10:11], s[42:43] offset:512
	v_pk_fma_f32 v[24:25], v[48:49], v[48:49], v[24:25]
	v_cvt_pk_bf16_f32 v12, v48, v49
	v_pk_fma_f32 v[24:25], v[50:51], v[50:51], v[24:25]
	v_cvt_pk_bf16_f32 v13, v50, v51
	global_store_dwordx2 v30, v[12:13], s[42:43] offset:1024
	v_pk_fma_f32 v[24:25], v[52:53], v[52:53], v[24:25]
	v_cvt_pk_bf16_f32 v14, v52, v53
	v_pk_fma_f32 v[24:25], v[54:55], v[54:55], v[24:25]
	v_cvt_pk_bf16_f32 v15, v54, v55
	global_store_dwordx2 v30, v[14:15], s[42:43] offset:1536
	v_pk_fma_f32 v[24:25], v[56:57], v[56:57], v[24:25]
	v_cvt_pk_bf16_f32 v16, v56, v57
	v_pk_fma_f32 v[24:25], v[58:59], v[58:59], v[24:25]
	v_cvt_pk_bf16_f32 v17, v58, v59
	global_store_dwordx2 v30, v[16:17], s[42:43] offset:2048
	v_pk_fma_f32 v[24:25], v[60:61], v[60:61], v[24:25]
	v_cvt_pk_bf16_f32 v18, v60, v61
	v_pk_fma_f32 v[24:25], v[62:63], v[62:63], v[24:25]
	v_cvt_pk_bf16_f32 v19, v62, v63
	global_store_dwordx2 v30, v[18:19], s[42:43] offset:2560
	v_pk_fma_f32 v[24:25], v[64:65], v[64:65], v[24:25]
	v_cvt_pk_bf16_f32 v20, v64, v65
	v_pk_fma_f32 v[24:25], v[66:67], v[66:67], v[24:25]
	v_cvt_pk_bf16_f32 v21, v66, v67
	global_store_dwordx2 v30, v[20:21], s[42:43] offset:3072
	v_pk_fma_f32 v[24:25], v[68:69], v[68:69], v[24:25]
	v_cvt_pk_bf16_f32 v22, v68, v69
	v_pk_fma_f32 v[24:25], v[70:71], v[70:71], v[24:25]
	v_cvt_pk_bf16_f32 v23, v70, v71
	global_store_dwordx2 v30, v[22:23], s[42:43] offset:3584
	v_add_f32_e32 v26, v24, v25
	s_nop 1
	v_add_f32_dpp v26, v26, v26 quad_perm:[1,0,3,2] row_mask:0xf bank_mask:0xf
	s_nop 1
	v_add_f32_dpp v26, v26, v26 quad_perm:[2,3,0,1] row_mask:0xf bank_mask:0xf
	s_nop 1
	v_add_f32_dpp v26, v26, v26 row_half_mirror row_mask:0xf bank_mask:0xf
	s_nop 1
	v_add_f32_dpp v26, v26, v26 row_mirror row_mask:0xf bank_mask:0xf
	s_nop 1
	v_add_f32_dpp v26, v26, v26 row_bcast:15 row_mask:0xa bank_mask:0xf
	s_nop 1
	v_add_f32_dpp v26, v26, v26 row_bcast:31 row_mask:0xc bank_mask:0xf
	s_nop 1
	v_readlane_b32 s24, v26, 63
	s_nop 3
	v_fma_f32 v26, s24, v32, v33
	v_rsq_f32_e32 v26, v26
	s_mov_b64 exec, 1
	s_nop 1
	global_store_dword v31, v26, s[50:51]
	s_mov_b64 exec, -1
	s_mov_b32 s9, s54
	s_add_i32 s54, s9, s14
	s_cmp_lt_u32 s54, 0x2000
	s_cbranch_scc0 .Lxc_lastB
; __device__ __forceinline__ unsigned cvt_pk_bf16(float lo, float hi) { unsigned r; asm volatile("v_cvt_pk_bf16_f32 %0, %1, %2" : "=v"(r) : "v"(lo), "v"(hi)); return r; }
; #define GAS __attribute__((address_space(1)))
; __device__ __forceinline__ void phase_prep(const Params& P, unsigned char* smem) {
;     ...
;     for (int rid = gw; rid < NSEG * RSB; rid += NGW) {
;         const int s = rid / RSB, lr = rid % RSB; const float* src = nullptr;
;         if (lr < RS) src = P.x + ((size_t)(lr / TSEG) * SEQ + (size_t)s * TSEG + (lr % TSEG)) * DM;
;         else if (s == 0) { if (lr >= RS + 48 && lr < RS + 64) src = P.meta + (size_t)(lr - RS - 48) * DM; }
;         else continue;
;         GAS v2u* o8 = (GAS v2u*)(xb + (size_t)rid * DM) + lane; float ss = 0.f;
;         if (src) { const f32x4* xr = (const f32x4*)src + lane;
; #pragma unroll
;             for (int j = 0; j < 8; ++j) { const f32x4 v = __builtin_nontemporal_load((const GAS f32x4*)xr + 64 * j); ss += (v[0] * v[0] + v[1] * v[1]) + (v[2] * v[2] + v[3] * v[3]); v2u o; o.x = cvt_pk_bf16(v[0], v[1]); o.y = cvt_pk_bf16(v[2], v[3]); o8[64 * j] = o; } }
;         else {
; #pragma unroll
;             for (int j = 0; j < 8; ++j) { v2u o; o.x = 0u; o.y = 0u; o8[64 * j] = o; } }
;         ss = wave_sum(ss);
;         if (lane == 0) rstd1[rid] = rsqrtf(ss * (1.f / DM) + EPS);
	s_lshr_b32 s20, s54, 12
	s_and_b32 s22, s54, 0xfff
	s_lshl_b32 s20, s20, 14
	s_add_i32 s20, s20, s22
	s_add_i32 s20, s20, s15
	s_lshl_b32 s20, s20, 13
	s_add_u32 s40, s16, s20
	s_addc_u32 s41, s17, 0
	global_load_dwordx4 v[40:43], v28, s[40:41] nt
	global_load_dwordx4 v[44:47], v28, s[40:41] offset:1024 nt
	global_load_dwordx4 v[48:51], v28, s[40:41] offset:2048 nt
	global_load_dwordx4 v[52:55], v28, s[40:41] offset:3072 nt
	global_load_dwordx4 v[56:59], v29, s[40:41] nt
	global_load_dwordx4 v[60:63], v29, s[40:41] offset:1024 nt
	global_load_dwordx4 v[64:67], v29, s[40:41] offset:2048 nt
	global_load_dwordx4 v[68:71], v29, s[40:41] offset:3072 nt
	s_waitcnt vmcnt(8)
	s_add_i32 s22, s9, s23
	s_lshl_b32 s24, s22, 12
	s_add_u32 s42, s48, s24
	s_addc_u32 s43, s49, 0
	s_lshl_b32 s24, s22, 2
	s_add_u32 s50, s52, s24
	s_addc_u32 s51, s53, 0
	v_pk_mul_f32 v[24:25], v[72:73], v[72:73]
	v_cvt_pk_bf16_f32 v8, v72, v73
	v_pk_fma_f32 v[24:25], v[74:75], v[74:75], v[24:25]
	v_cvt_pk_bf16_f32 v9, v74, v75
	global_store_dwordx2 v30, v[8:9], s[42:43]
	v_pk_fma_f32 v[24:25], v[76:77], v[76:77], v[24:25]
	v_cvt_pk_bf16_f32 v10, v76, v77
	v_pk_fma_f32 v[24:25], v[78:79], v[78:79], v[24:25]
	v_cvt_pk_bf16_f32 v11, v78, v79
	global_store_dwordx2 v30, v[10:11], s[42:43] offset:512
	v_pk_fma_f32 v[24:25], v[80:81], v[80:81], v[24:25]
	v_cvt_pk_bf16_f32 v12, v80, v81
	v_pk_fma_f32 v[24:25], v[82:83], v[82:83], v[24:25]
	v_cvt_pk_bf16_f32 v13, v82, v83
	global_store_dwordx2 v30, v[12:13], s[42:43] offset:1024
	v_pk_fma_f32 v[24:25], v[84:85], v[84:85], v[24:25]
	v_cvt_pk_bf16_f32 v14, v84, v85
	v_pk_fma_f32 v[24:25], v[86:87], v[86:87], v[24:25]
	v_cvt_pk_bf16_f32 v15, v86, v87
	global_store_dwordx2 v30, v[14:15], s[42:43] offset:1536
	v_pk_fma_f32 v[24:25], v[88:89], v[88:89], v[24:25]
	v_cvt_pk_bf16_f32 v16, v88, v89
	v_pk_fma_f32 v[24:25], v[90:91], v[90:91], v[24:25]
	v_cvt_pk_bf16_f32 v17, v90, v91
	global_store_dwordx2 v30, v[16:17], s[42:43] offset:2048
	v_pk_fma_f32 v[24:25], v[92:93], v[92:93], v[24:25]
	v_cvt_pk_bf16_f32 v18, v92, v93
	v_pk_fma_f32 v[24:25], v[94:95], v[94:95], v[24:25]
	v_cvt_pk_bf16_f32 v19, v94, v95
	global_store_dwordx2 v30, v[18:19], s[42:43] offset:2560
	v_pk_fma_f32 v[24:25], v[96:97], v[96:97], v[24:25]
	v_cvt_pk_bf16_f32 v20, v96, v97
	v_pk_fma_f32 v[24:25], v[98:99], v[98:99], v[24:25]
	v_cvt_pk_bf16_f32 v21, v98, v99
	global_store_dwordx2 v30, v[20:21], s[42:43] offset:3072
	v_pk_fma_f32 v[24:25], v[100:101], v[100:101], v[24:25]
	v_cvt_pk_bf16_f32 v22, v100, v101
	v_pk_fma_f32 v[24:25], v[102:103], v[102:103], v[24:25]
	v_cvt_pk_bf16_f32 v23, v102, v103
	global_store_dwordx2 v30, v[22:23], s[42:43] offset:3584
	v_add_f32_e32 v26, v24, v25
	s_nop 1
	v_add_f32_dpp v26, v26, v26 quad_perm:[1,0,3,2] row_mask:0xf bank_mask:0xf
	s_nop 1
	v_add_f32_dpp v26, v26, v26 quad_perm:[2,3,0,1] row_mask:0xf bank_mask:0xf
	s_nop 1
	v_add_f32_dpp v26, v26, v26 row_half_mirror row_mask:0xf bank_mask:0xf
	s_nop 1
	v_add_f32_dpp v26, v26, v26 row_mirror row_mask:0xf bank_mask:0xf
	s_nop 1
	v_add_f32_dpp v26, v26, v26 row_bcast:15 row_mask:0xa bank_mask:0xf
	s_nop 1
	v_add_f32_dpp v26, v26, v26 row_bcast:31 row_mask:0xc bank_mask:0xf
	s_nop 1
	v_readlane_b32 s24, v26, 63
	s_nop 3
	v_fma_f32 v26, s24, v32, v33
	v_rsq_f32_e32 v26, v26
	s_mov_b64 exec, 1
	s_nop 1
	global_store_dword v31, v26, s[50:51]
	s_mov_b64 exec, -1
	s_mov_b32 s9, s54
	s_branch .Lxc_loop
; __device__ __forceinline__ unsigned cvt_pk_bf16(float lo, float hi) { unsigned r; asm volatile("v_cvt_pk_bf16_f32 %0, %1, %2" : "=v"(r) : "v"(lo), "v"(hi)); return r; }
; #define GAS __attribute__((address_space(1)))
; __device__ __forceinline__ void phase_prep(const Params& P, unsigned char* smem) {
;     ...
;     for (int rid = gw; rid < NSEG * RSB; rid += NGW) {
;         const int s = rid / RSB, lr = rid % RSB; const float* src = nullptr;
;         if (lr < RS) src = P.x + ((size_t)(lr / TSEG) * SEQ + (size_t)s * TSEG + (lr % TSEG)) * DM;
;         else if (s == 0) { if (lr >= RS + 48 && lr < RS + 64) src = P.meta + (size_t)(lr - RS - 48) * DM; }
;         else continue;
;         GAS v2u* o8 = (GAS v2u*)(xb + (size_t)rid * DM) + lane; float ss = 0.f;
;         if (src) { const f32x4* xr = (const f32x4*)src + lane;
; #pragma unroll
;             for (int j = 0; j < 8; ++j) { const f32x4 v = __builtin_nontemporal_load((const GAS f32x4*)xr + 64 * j); ss += (v[0] * v[0] + v[1] * v[1]) + (v[2] * v[2] + v[3] * v[3]); v2u o; o.x = cvt_pk_bf16(v[0], v[1]); o.y = cvt_pk_bf16(v[2], v[3]); o8[64 * j] = o; } }
;         else {
; #pragma unroll
;             for (int j = 0; j < 8; ++j) { v2u o; o.x = 0u; o.y = 0u; o8[64 * j] = o; } }
;         ss = wave_sum(ss);
;         if (lane == 0) rstd1[rid] = rsqrtf(ss * (1.f / DM) + EPS);
.Lxc_lastA:
	s_waitcnt vmcnt(0)
	s_add_i32 s22, s9, s23
	s_lshl_b32 s24, s22, 12
	s_add_u32 s42, s48, s24
	s_addc_u32 s43, s49, 0
	s_lshl_b32 s24, s22, 2
	s_add_u32 s50, s52, s24
	s_addc_u32 s51, s53, 0
	v_pk_mul_f32 v[24:25], v[40:41], v[40:41]
	v_cvt_pk_bf16_f32 v8, v40, v41
	v_pk_fma_f32 v[24:25], v[42:43], v[42:43], v[24:25]
	v_cvt_pk_bf16_f32 v9, v42, v43
	global_store_dwordx2 v30, v[8:9], s[42:43]
	v_pk_fma_f32 v[24:25], v[44:45], v[44:45], v[24:25]
	v_cvt_pk_bf16_f32 v10, v44, v45
	v_pk_fma_f32 v[24:25], v[46:47], v[46:47], v[24:25]
	v_cvt_pk_bf16_f32 v11, v46, v47
	global_store_dwordx2 v30, v[10:11], s[42:43] offset:512
	v_pk_fma_f32 v[24:25], v[48:49], v[48:49], v[24:25]
	v_cvt_pk_bf16_f32 v12, v48, v49
	v_pk_fma_f32 v[24:25], v[50:51], v[50:51], v[24:25]
	v_cvt_pk_bf16_f32 v13, v50, v51
	global_store_dwordx2 v30, v[12:13], s[42:43] offset:1024
	v_pk_fma_f32 v[24:25], v[52:53], v[52:53], v[24:25]
	v_cvt_pk_bf16_f32 v14, v52, v53
	v_pk_fma_f32 v[24:25], v[54:55], v[54:55], v[24:25]
	v_cvt_pk_bf16_f32 v15, v54, v55
	global_store_dwordx2 v30, v[14:15], s[42:43] offset:1536
	v_pk_fma_f32 v[24:25], v[56:57], v[56:57], v[24:25]
	v_cvt_pk_bf16_f32 v16, v56, v57
	v_pk_fma_f32 v[24:25], v[58:59], v[58:59], v[24:25]
	v_cvt_pk_bf16_f32 v17, v58, v59
	global_store_dwordx2 v30, v[16:17], s[42:43] offset:2048
	v_pk_fma_f32 v[24:25], v[60:61], v[60:61], v[24:25]
	v_cvt_pk_bf16_f32 v18, v60, v61
	v_pk_fma_f32 v[24:25], v[62:63], v[62:63], v[24:25]
	v_cvt_pk_bf16_f32 v19, v62, v63
	global_store_dwordx2 v30, v[18:19], s[42:43] offset:2560
	v_pk_fma_f32 v[24:25], v[64:65], v[64:65], v[24:25]
	v_cvt_pk_bf16_f32 v20, v64, v65
	v_pk_fma_f32 v[24:25], v[66:67], v[66:67], v[24:25]
	v_cvt_pk_bf16_f32 v21, v66, v67
	global_store_dwordx2 v30, v[20:21], s[42:43] offset:3072
	v_pk_fma_f32 v[24:25], v[68:69], v[68:69], v[24:25]
	v_cvt_pk_bf16_f32 v22, v68, v69
	v_pk_fma_f32 v[24:25], v[70:71], v[70:71], v[24:25]
	v_cvt_pk_bf16_f32 v23, v70, v71
	global_store_dwordx2 v30, v[22:23], s[42:43] offset:3584
	v_add_f32_e32 v26, v24, v25
	s_nop 1
	v_add_f32_dpp v26, v26, v26 quad_perm:[1,0,3,2] row_mask:0xf bank_mask:0xf
	s_nop 1
	v_add_f32_dpp v26, v26, v26 quad_perm:[2,3,0,1] row_mask:0xf bank_mask:0xf
	s_nop 1
	v_add_f32_dpp v26, v26, v26 row_half_mirror row_mask:0xf bank_mask:0xf
	s_nop 1
	v_add_f32_dpp v26, v26, v26 row_mirror row_mask:0xf bank_mask:0xf
	s_nop 1
	v_add_f32_dpp v26, v26, v26 row_bcast:15 row_mask:0xa bank_mask:0xf
	s_nop 1
	v_add_f32_dpp v26, v26, v26 row_bcast:31 row_mask:0xc bank_mask:0xf
	s_nop 1
	v_readlane_b32 s24, v26, 63
	s_nop 3
	v_fma_f32 v26, s24, v32, v33
	v_rsq_f32_e32 v26, v26
	s_mov_b64 exec, 1
	s_nop 1
	global_store_dword v31, v26, s[50:51]
	s_mov_b64 exec, -1
	s_branch .Lxc_exit
.Lxc_lastB:
	s_waitcnt vmcnt(0)
	s_add_i32 s22, s9, s23
	s_lshl_b32 s24, s22, 12
	s_add_u32 s42, s48, s24
	s_addc_u32 s43, s49, 0
	s_lshl_b32 s24, s22, 2
	s_add_u32 s50, s52, s24
	s_addc_u32 s51, s53, 0
	v_pk_mul_f32 v[24:25], v[72:73], v[72:73]
	v_cvt_pk_bf16_f32 v8, v72, v73
	v_pk_fma_f32 v[24:25], v[74:75], v[74:75], v[24:25]
	v_cvt_pk_bf16_f32 v9, v74, v75
	global_store_dwordx2 v30, v[8:9], s[42:43]
	v_pk_fma_f32 v[24:25], v[76:77], v[76:77], v[24:25]
	v_cvt_pk_bf16_f32 v10, v76, v77
	v_pk_fma_f32 v[24:25], v[78:79], v[78:79], v[24:25]
	v_cvt_pk_bf16_f32 v11, v78, v79
	global_store_dwordx2 v30, v[10:11], s[42:43] offset:512
	v_pk_fma_f32 v[24:25], v[80:81], v[80:81], v[24:25]
	v_cvt_pk_bf16_f32 v12, v80, v81
	v_pk_fma_f32 v[24:25], v[82:83], v[82:83], v[24:25]
	v_cvt_pk_bf16_f32 v13, v82, v83
	global_store_dwordx2 v30, v[12:13], s[42:43] offset:1024
	v_pk_fma_f32 v[24:25], v[84:85], v[84:85], v[24:25]
	v_cvt_pk_bf16_f32 v14, v84, v85
	v_pk_fma_f32 v[24:25], v[86:87], v[86:87], v[24:25]
	v_cvt_pk_bf16_f32 v15, v86, v87
	global_store_dwordx2 v30, v[14:15], s[42:43] offset:1536
	v_pk_fma_f32 v[24:25], v[88:89], v[88:89], v[24:25]
	v_cvt_pk_bf16_f32 v16, v88, v89
	v_pk_fma_f32 v[24:25], v[90:91], v[90:91], v[24:25]
	v_cvt_pk_bf16_f32 v17, v90, v91
	global_store_dwordx2 v30, v[16:17], s[42:43] offset:2048
	v_pk_fma_f32 v[24:25], v[92:93], v[92:93], v[24:25]
	v_cvt_pk_bf16_f32 v18, v92, v93
	v_pk_fma_f32 v[24:25], v[94:95], v[94:95], v[24:25]
	v_cvt_pk_bf16_f32 v19, v94, v95
	global_store_dwordx2 v30, v[18:19], s[42:43] offset:2560
	v_pk_fma_f32 v[24:25], v[96:97], v[96:97], v[24:25]
	v_cvt_pk_bf16_f32 v20, v96, v97
	v_pk_fma_f32 v[24:25], v[98:99], v[98:99], v[24:25]
	v_cvt_pk_bf16_f32 v21, v98, v99
	global_store_dwordx2 v30, v[20:21], s[42:43] offset:3072
	v_pk_fma_f32 v[24:25], v[100:101], v[100:101], v[24:25]
	v_cvt_pk_bf16_f32 v22, v100, v101
	v_pk_fma_f32 v[24:25], v[102:103], v[102:103], v[24:25]
	v_cvt_pk_bf16_f32 v23, v102, v103
	global_store_dwordx2 v30, v[22:23], s[42:43] offset:3584
	v_add_f32_e32 v26, v24, v25
	s_nop 1
	v_add_f32_dpp v26, v26, v26 quad_perm:[1,0,3,2] row_mask:0xf bank_mask:0xf
	s_nop 1
	v_add_f32_dpp v26, v26, v26 quad_perm:[2,3,0,1] row_mask:0xf bank_mask:0xf
	s_nop 1
	v_add_f32_dpp v26, v26, v26 row_half_mirror row_mask:0xf bank_mask:0xf
	s_nop 1
	v_add_f32_dpp v26, v26, v26 row_mirror row_mask:0xf bank_mask:0xf
	s_nop 1
	v_add_f32_dpp v26, v26, v26 row_bcast:15 row_mask:0xa bank_mask:0xf
	s_nop 1
	v_add_f32_dpp v26, v26, v26 row_bcast:31 row_mask:0xc bank_mask:0xf
	s_nop 1
	v_readlane_b32 s24, v26, 63
	s_nop 3
	v_fma_f32 v26, s24, v32, v33
	v_rsq_f32_e32 v26, v26
	s_mov_b64 exec, 1
	s_nop 1
	global_store_dword v31, v26, s[50:51]
	s_mov_b64 exec, -1
.Lxc_exit:
	s_mov_b64 exec, s[36:37]
